# attention tile loop: comp-0 rare blocks moved out of line (hot loop contiguous)
# baseline (speedup 1.0000x reference)
.Lat_rare0a:
	v_max3_f32 v17, v162, v163, v164
	v_max3_f32 v17, v17, v165, v166
	v_max3_f32 v17, v17, v167, v168
	v_max3_f32 v17, v17, v169, v170
	v_max3_f32 v17, v17, v171, v172
	v_max3_f32 v17, v17, v173, v174
	v_max3_f32 v17, v17, v175, v176
	v_max_f32_e32 v17, v17, v177
	v_mov_b32_e32 v219, v17
	s_nop 1
	v_permlane32_swap_b32_e32 v17, v219
	v_max_f32_e32 v17, v17, v219
	v_mul_f32_e32 v17, s97, v17
	v_max_f32_e32 v219, v207, v17
	v_sub_f32_e32 v216, v207, v219
	v_exp_f32_e32 v216, v216
	v_mov_b32_e32 v207, v219
	s_nop 0
	v_pk_mul_f32 v[144:145], v[144:145], v[216:217] op_sel_hi:[1,0]
	v_pk_mul_f32 v[142:143], v[142:143], v[216:217] op_sel_hi:[1,0]
	v_pk_mul_f32 v[140:141], v[140:141], v[216:217] op_sel_hi:[1,0]
	v_pk_mul_f32 v[138:139], v[138:139], v[216:217] op_sel_hi:[1,0]
	v_pk_mul_f32 v[136:137], v[136:137], v[216:217] op_sel_hi:[1,0]
	v_pk_mul_f32 v[134:135], v[134:135], v[216:217] op_sel_hi:[1,0]
	v_pk_mul_f32 v[132:133], v[132:133], v[216:217] op_sel_hi:[1,0]
	v_pk_mul_f32 v[130:131], v[130:131], v[216:217] op_sel_hi:[1,0]
	v_pk_mul_f32 v[112:113], v[112:113], v[216:217] op_sel_hi:[1,0]
	v_pk_mul_f32 v[110:111], v[110:111], v[216:217] op_sel_hi:[1,0]
	v_pk_mul_f32 v[108:109], v[108:109], v[216:217] op_sel_hi:[1,0]
	v_pk_mul_f32 v[106:107], v[106:107], v[216:217] op_sel_hi:[1,0]
	v_pk_mul_f32 v[104:105], v[104:105], v[216:217] op_sel_hi:[1,0]
	v_pk_mul_f32 v[102:103], v[102:103], v[216:217] op_sel_hi:[1,0]
	v_pk_mul_f32 v[100:101], v[100:101], v[216:217] op_sel_hi:[1,0]
	v_pk_mul_f32 v[98:99], v[98:99], v[216:217] op_sel_hi:[1,0]
	v_pk_mul_f32 v[80:81], v[80:81], v[216:217] op_sel_hi:[1,0]
	v_pk_mul_f32 v[78:79], v[78:79], v[216:217] op_sel_hi:[1,0]
	v_pk_mul_f32 v[76:77], v[76:77], v[216:217] op_sel_hi:[1,0]
	v_pk_mul_f32 v[74:75], v[74:75], v[216:217] op_sel_hi:[1,0]
	v_pk_mul_f32 v[72:73], v[72:73], v[216:217] op_sel_hi:[1,0]
	v_pk_mul_f32 v[70:71], v[70:71], v[216:217] op_sel_hi:[1,0]
	v_pk_mul_f32 v[68:69], v[68:69], v[216:217] op_sel_hi:[1,0]
	v_pk_mul_f32 v[66:67], v[66:67], v[216:217] op_sel_hi:[1,0]
	v_pk_mul_f32 v[48:49], v[48:49], v[216:217] op_sel_hi:[1,0]
	v_pk_mul_f32 v[46:47], v[46:47], v[216:217] op_sel_hi:[1,0]
	v_pk_mul_f32 v[44:45], v[44:45], v[216:217] op_sel_hi:[1,0]
	v_pk_mul_f32 v[42:43], v[42:43], v[216:217] op_sel_hi:[1,0]
	v_pk_mul_f32 v[40:41], v[40:41], v[216:217] op_sel_hi:[1,0]
	v_pk_mul_f32 v[38:39], v[38:39], v[216:217] op_sel_hi:[1,0]
	v_pk_mul_f32 v[36:37], v[36:37], v[216:217] op_sel_hi:[1,0]
	v_pk_mul_f32 v[34:35], v[34:35], v[216:217] op_sel_hi:[1,0]
	v_mul_f32_e32 v186, v186, v216
	v_fma_f32 v216, v162, s97, -v207
	v_fma_f32 v217, v163, s97, -v207
	v_fma_f32 v252, v164, s97, -v207
	v_fma_f32 v253, v165, s97, -v207
	v_exp_f32_e32 v216, v216
	v_exp_f32_e32 v217, v217
	v_exp_f32_e32 v252, v252
	v_exp_f32_e32 v253, v253
	v_cvt_pk_bf16_f32 v178, v216, v217
	v_cvt_pk_bf16_f32 v179, v252, v253
	v_add_f32_e32 v17, v252, v216
	v_add_f32_e32 v219, v253, v217
	v_fma_f32 v216, v166, s97, -v207
	v_fma_f32 v217, v167, s97, -v207
	v_fma_f32 v252, v168, s97, -v207
	v_fma_f32 v253, v169, s97, -v207
	v_exp_f32_e32 v216, v216
	v_exp_f32_e32 v217, v217
	v_exp_f32_e32 v252, v252
	v_exp_f32_e32 v253, v253
	v_add_f32_e32 v17, v216, v17
	v_add_f32_e32 v219, v217, v219
	v_cvt_pk_bf16_f32 v180, v216, v217
	v_cvt_pk_bf16_f32 v181, v252, v253
	v_add_f32_e32 v17, v252, v17
	v_add_f32_e32 v219, v253, v219
	v_fma_f32 v216, v170, s97, -v207
	v_fma_f32 v217, v171, s97, -v207
	v_fma_f32 v252, v172, s97, -v207
	v_fma_f32 v253, v173, s97, -v207
	v_exp_f32_e32 v216, v216
	v_exp_f32_e32 v217, v217
	v_exp_f32_e32 v252, v252
	v_exp_f32_e32 v253, v253
	v_add_f32_e32 v17, v216, v17
	v_add_f32_e32 v219, v217, v219
	v_cvt_pk_bf16_f32 v12, v216, v217
	v_cvt_pk_bf16_f32 v13, v252, v253
	v_add_f32_e32 v17, v252, v17
	v_add_f32_e32 v219, v253, v219
	v_fma_f32 v216, v174, s97, -v207
	v_fma_f32 v217, v175, s97, -v207
	v_fma_f32 v252, v176, s97, -v207
	v_fma_f32 v253, v177, s97, -v207
	v_exp_f32_e32 v216, v216
	v_exp_f32_e32 v217, v217
	v_exp_f32_e32 v252, v252
	v_exp_f32_e32 v253, v253
	v_add_f32_e32 v17, v216, v17
	v_add_f32_e32 v219, v217, v219
	v_cvt_pk_bf16_f32 v14, v216, v217
	v_cvt_pk_bf16_f32 v15, v252, v253
	v_add_f32_e32 v17, v252, v17
	v_add_f32_e32 v219, v253, v219
	v_add_f32_e32 v17, v17, v219
	s_branch .Lat_ok0a
.Lat_rare0b:
	s_nop 15
	s_nop 15
	v_max3_f32 v254, v146, v147, v148
	v_max3_f32 v254, v254, v149, v150
	v_max3_f32 v254, v254, v151, v152
	v_max3_f32 v254, v254, v153, v154
	v_max3_f32 v254, v254, v155, v156
	v_max3_f32 v254, v254, v157, v158
	v_max3_f32 v254, v254, v159, v160
	v_max_f32_e32 v254, v254, v161
	v_mov_b32_e32 v204, v254
	s_nop 1
	v_permlane32_swap_b32_e32 v254, v204
	v_max_f32_e32 v254, v254, v204
	v_mul_f32_e32 v254, s97, v254
	v_max_f32_e32 v204, v207, v254
	v_sub_f32_e32 v216, v207, v204
	v_exp_f32_e32 v216, v216
	v_mov_b32_e32 v207, v204
	s_nop 0
	v_pk_mul_f32 v[144:145], v[144:145], v[216:217] op_sel_hi:[1,0]
	v_pk_mul_f32 v[142:143], v[142:143], v[216:217] op_sel_hi:[1,0]
	v_pk_mul_f32 v[140:141], v[140:141], v[216:217] op_sel_hi:[1,0]
	v_pk_mul_f32 v[138:139], v[138:139], v[216:217] op_sel_hi:[1,0]
	v_pk_mul_f32 v[136:137], v[136:137], v[216:217] op_sel_hi:[1,0]
	v_pk_mul_f32 v[134:135], v[134:135], v[216:217] op_sel_hi:[1,0]
	v_pk_mul_f32 v[132:133], v[132:133], v[216:217] op_sel_hi:[1,0]
	v_pk_mul_f32 v[130:131], v[130:131], v[216:217] op_sel_hi:[1,0]
	v_pk_mul_f32 v[112:113], v[112:113], v[216:217] op_sel_hi:[1,0]
	v_pk_mul_f32 v[110:111], v[110:111], v[216:217] op_sel_hi:[1,0]
	v_pk_mul_f32 v[108:109], v[108:109], v[216:217] op_sel_hi:[1,0]
	v_pk_mul_f32 v[106:107], v[106:107], v[216:217] op_sel_hi:[1,0]
	v_pk_mul_f32 v[104:105], v[104:105], v[216:217] op_sel_hi:[1,0]
	v_pk_mul_f32 v[102:103], v[102:103], v[216:217] op_sel_hi:[1,0]
	v_pk_mul_f32 v[100:101], v[100:101], v[216:217] op_sel_hi:[1,0]
	v_pk_mul_f32 v[98:99], v[98:99], v[216:217] op_sel_hi:[1,0]
	v_pk_mul_f32 v[80:81], v[80:81], v[216:217] op_sel_hi:[1,0]
	v_pk_mul_f32 v[78:79], v[78:79], v[216:217] op_sel_hi:[1,0]
	v_pk_mul_f32 v[76:77], v[76:77], v[216:217] op_sel_hi:[1,0]
	v_pk_mul_f32 v[74:75], v[74:75], v[216:217] op_sel_hi:[1,0]
	v_pk_mul_f32 v[72:73], v[72:73], v[216:217] op_sel_hi:[1,0]
	v_pk_mul_f32 v[70:71], v[70:71], v[216:217] op_sel_hi:[1,0]
	v_pk_mul_f32 v[68:69], v[68:69], v[216:217] op_sel_hi:[1,0]
	v_pk_mul_f32 v[66:67], v[66:67], v[216:217] op_sel_hi:[1,0]
	v_pk_mul_f32 v[48:49], v[48:49], v[216:217] op_sel_hi:[1,0]
	v_pk_mul_f32 v[46:47], v[46:47], v[216:217] op_sel_hi:[1,0]
	v_pk_mul_f32 v[44:45], v[44:45], v[216:217] op_sel_hi:[1,0]
	v_pk_mul_f32 v[42:43], v[42:43], v[216:217] op_sel_hi:[1,0]
	v_pk_mul_f32 v[40:41], v[40:41], v[216:217] op_sel_hi:[1,0]
	v_pk_mul_f32 v[38:39], v[38:39], v[216:217] op_sel_hi:[1,0]
	v_pk_mul_f32 v[36:37], v[36:37], v[216:217] op_sel_hi:[1,0]
	v_pk_mul_f32 v[34:35], v[34:35], v[216:217] op_sel_hi:[1,0]
	v_mul_f32_e32 v186, v186, v216
	v_fma_f32 v216, v146, s97, -v207
	v_fma_f32 v217, v147, s97, -v207
	v_fma_f32 v252, v148, s97, -v207
	v_fma_f32 v253, v149, s97, -v207
	v_exp_f32_e32 v216, v216
	v_exp_f32_e32 v217, v217
	v_exp_f32_e32 v252, v252
	v_exp_f32_e32 v253, v253
	v_cvt_pk_bf16_f32 v8, v216, v217
	v_cvt_pk_bf16_f32 v9, v252, v253
	v_add_f32_e32 v254, v252, v216
	v_add_f32_e32 v204, v253, v217
	v_fma_f32 v216, v150, s97, -v207
	v_fma_f32 v217, v151, s97, -v207
	v_fma_f32 v252, v152, s97, -v207
	v_fma_f32 v253, v153, s97, -v207
	v_exp_f32_e32 v216, v216
	v_exp_f32_e32 v217, v217
	v_exp_f32_e32 v252, v252
	v_exp_f32_e32 v253, v253
	v_add_f32_e32 v254, v216, v254
	v_add_f32_e32 v204, v217, v204
	v_cvt_pk_bf16_f32 v10, v216, v217
	v_cvt_pk_bf16_f32 v11, v252, v253
	v_add_f32_e32 v254, v252, v254
	v_add_f32_e32 v204, v253, v204
	v_fma_f32 v216, v154, s97, -v207
	v_fma_f32 v217, v155, s97, -v207
	v_fma_f32 v252, v156, s97, -v207
	v_fma_f32 v253, v157, s97, -v207
	v_exp_f32_e32 v216, v216
	v_exp_f32_e32 v217, v217
	v_exp_f32_e32 v252, v252
	v_exp_f32_e32 v253, v253
	v_add_f32_e32 v254, v216, v254
	v_add_f32_e32 v204, v217, v204
	v_cvt_pk_bf16_f32 v4, v216, v217
	v_cvt_pk_bf16_f32 v5, v252, v253
	v_add_f32_e32 v254, v252, v254
	v_add_f32_e32 v204, v253, v204
	v_fma_f32 v216, v158, s97, -v207
	v_fma_f32 v217, v159, s97, -v207
	v_fma_f32 v252, v160, s97, -v207
	v_fma_f32 v253, v161, s97, -v207
	v_exp_f32_e32 v216, v216
	v_exp_f32_e32 v217, v217
	v_exp_f32_e32 v252, v252
	v_exp_f32_e32 v253, v253
	v_add_f32_e32 v254, v216, v254
	v_add_f32_e32 v204, v217, v204
	v_cvt_pk_bf16_f32 v6, v216, v217
	v_cvt_pk_bf16_f32 v7, v252, v253
	v_add_f32_e32 v254, v252, v254
	v_add_f32_e32 v204, v253, v204
	v_add_f32_e32 v254, v254, v204
	s_branch .Lat_ok0b

.LBB0_711:
	s_cmp_ge_u32 s55, s78
	s_cbranch_scc1 .LBB0_717
	s_and_b32 s55, s50, 0x4000
	v_add_u32_e32 v16, s55, v198
	v_add_u32_e32 v216, v199, v16
	ds_read_b128 v[220:223], v216
	ds_read_b128 v[224:227], v216 offset:8192
	ds_read_b128 v[228:231], v205
	v_xad_u32 v217, v199, 32, v16
	ds_read_b128 v[232:235], v217
	ds_read_b128 v[236:239], v217 offset:8192
	ds_read_b128 v[240:243], v205 offset:32
	v_xad_u32 v216, v199, 64, v16
	ds_read_b128 v[244:247], v216
	ds_read_b128 v[248:251], v216 offset:8192
	ds_read_b128 v[200:203], v205 offset:64
	v_xad_u32 v217, v199, s79, v16
	ds_read_b128 v[208:211], v217
	ds_read_b128 v[212:215], v217 offset:8192
	s_waitcnt lgkmcnt(8)
	v_mfma_f32_32x32x16_bf16 v[162:177], v[220:223], v[228:231], 0
	v_mfma_f32_32x32x16_bf16 v[146:161], v[224:227], v[228:231], 0
	ds_read_b128 v[220:223], v205 offset:96
	s_waitcnt lgkmcnt(6)
	v_mfma_f32_32x32x16_bf16 v[162:177], v[232:235], v[240:243], v[162:177]
	v_mfma_f32_32x32x16_bf16 v[146:161], v[236:239], v[240:243], v[146:161]
	s_waitcnt lgkmcnt(3)
	v_mfma_f32_32x32x16_bf16 v[162:177], v[244:247], v[200:203], v[162:177]
	v_mfma_f32_32x32x16_bf16 v[146:161], v[248:251], v[200:203], v[146:161]
	s_waitcnt lgkmcnt(0)
	v_mfma_f32_32x32x16_bf16 v[162:177], v[208:211], v[220:223], v[162:177]
	v_mfma_f32_32x32x16_bf16 v[146:161], v[212:215], v[220:223], v[146:161]
	v_xad_u32 v254, v199, s80, v16
	ds_read_b128 v[200:203], v254
	ds_read_b128 v[208:211], v254 offset:8192
	ds_read_b128 v[212:215], v205 offset:128
	s_nop 7
	v_fma_f32 v216, v162, s97, -v207
	v_fma_f32 v217, v163, s97, -v207
	v_fma_f32 v252, v164, s97, -v207
	v_fma_f32 v253, v165, s97, -v207
	v_exp_f32_e32 v216, v216
	v_exp_f32_e32 v217, v217
	v_exp_f32_e32 v252, v252
	v_exp_f32_e32 v253, v253
	v_cvt_pk_bf16_f32 v178, v216, v217
	v_cvt_pk_bf16_f32 v179, v252, v253
	v_add_f32_e32 v17, v252, v216
	v_add_f32_e32 v219, v253, v217
	s_waitcnt lgkmcnt(0)
	v_mfma_f32_32x32x16_bf16 v[220:235], v[200:203], v[212:215], 0
	v_mfma_f32_32x32x16_bf16 v[236:251], v[208:211], v[212:215], 0
	v_xad_u32 v204, v199, s81, v16
	ds_read_b128 v[200:203], v204
	ds_read_b128 v[208:211], v204 offset:8192
	ds_read_b128 v[212:215], v205 offset:160
	v_fma_f32 v216, v166, s97, -v207
	v_fma_f32 v217, v167, s97, -v207
	v_fma_f32 v252, v168, s97, -v207
	v_fma_f32 v253, v169, s97, -v207
	v_exp_f32_e32 v216, v216
	v_exp_f32_e32 v217, v217
	v_exp_f32_e32 v252, v252
	v_exp_f32_e32 v253, v253
	v_add_f32_e32 v17, v216, v17
	v_add_f32_e32 v219, v217, v219
	v_cvt_pk_bf16_f32 v180, v216, v217
	v_cvt_pk_bf16_f32 v181, v252, v253
	v_add_f32_e32 v17, v252, v17
	v_add_f32_e32 v219, v253, v219
	s_waitcnt lgkmcnt(0)
	v_mfma_f32_32x32x16_bf16 v[220:235], v[200:203], v[212:215], v[220:235]
	v_mfma_f32_32x32x16_bf16 v[236:251], v[208:211], v[212:215], v[236:251]
	v_xad_u32 v254, v199, s82, v16
	ds_read_b128 v[200:203], v254
	ds_read_b128 v[208:211], v254 offset:8192
	ds_read_b128 v[212:215], v205 offset:192
	v_fma_f32 v216, v170, s97, -v207
	v_fma_f32 v217, v171, s97, -v207
	v_fma_f32 v252, v172, s97, -v207
	v_fma_f32 v253, v173, s97, -v207
	v_exp_f32_e32 v216, v216
	v_exp_f32_e32 v217, v217
	v_exp_f32_e32 v252, v252
	v_exp_f32_e32 v253, v253
	v_add_f32_e32 v17, v216, v17
	v_add_f32_e32 v219, v217, v219
	v_cvt_pk_bf16_f32 v12, v216, v217
	v_cvt_pk_bf16_f32 v13, v252, v253
	v_add_f32_e32 v17, v252, v17
	v_add_f32_e32 v219, v253, v219
	s_waitcnt lgkmcnt(0)
	v_mfma_f32_32x32x16_bf16 v[220:235], v[200:203], v[212:215], v[220:235]
	v_mfma_f32_32x32x16_bf16 v[236:251], v[208:211], v[212:215], v[236:251]
	v_xad_u32 v204, v199, s83, v16
	ds_read_b128 v[200:203], v204
	ds_read_b128 v[208:211], v204 offset:8192
	ds_read_b128 v[212:215], v205 offset:224
	v_fma_f32 v216, v174, s97, -v207
	v_fma_f32 v217, v175, s97, -v207
	v_fma_f32 v252, v176, s97, -v207
	v_fma_f32 v253, v177, s97, -v207
	v_exp_f32_e32 v216, v216
	v_exp_f32_e32 v217, v217
	v_exp_f32_e32 v252, v252
	v_exp_f32_e32 v253, v253
	v_add_f32_e32 v17, v216, v17
	v_add_f32_e32 v219, v217, v219
	v_cvt_pk_bf16_f32 v14, v216, v217
	v_cvt_pk_bf16_f32 v15, v252, v253
	v_add_f32_e32 v17, v252, v17
	v_add_f32_e32 v219, v253, v219
	s_waitcnt lgkmcnt(0)
	v_mfma_f32_32x32x16_bf16 v[220:235], v[200:203], v[212:215], v[220:235]
	v_mfma_f32_32x32x16_bf16 v[236:251], v[208:211], v[212:215], v[236:251]
	v_add_f32_e32 v17, v17, v219
	v_cmp_lt_f32_e32 vcc, 0x43800000, v17
	s_cmp_lg_u64 vcc, 0
	s_cbranch_scc1 .Lat_rare0a

; DI void attn_item(const Params& p, char* smem, u16* qbase, const u16* gabase, const u16* kbase, const u16* vtbase,
;                   int tkv, int nkt, int mylimit, const float* lam_p, const int g_wave) {
;     ...
; #pragma unroll
;       for (int d = 0; d < 4; ++d) {
;         const int vrow = 32 * d + r;
; #pragma unroll
;         for (int sp = 0; sp < 4; ++sp) {
;           const u32x2 lo = *(const u32x2*)(Vt + vrow * 128 + ((32 * sp) ^ vz) + 8 * hh);
;           const u32x2 hi = *(const u32x2*)(Vt + vrow * 128 + ((32 * sp + 16) ^ vz) + 8 * hh);
;           u32x4 w = {lo[0], lo[1], hi[0], hi[1]};
;           const bf16x8 vf = *reinterpret_cast<bf16x8*>(&w);
;           O0[d] = __builtin_amdgcn_mfma_f32_32x32x16_bf16(vf, pf0[sp], O0[d], 0, 0, 0);
;           O1[d] = __builtin_amdgcn_mfma_f32_32x32x16_bf16(vf, pf1[sp], O1[d], 0, 0, 0);
;         }
;         __builtin_amdgcn_sched_barrier(0);
;       }
.Lat_nr1:
	s_waitcnt lgkmcnt(1)
	v_mfma_f32_32x32x16_bf16 v[66:81], v[170:173], v[178:181], v[66:81]
	v_fma_f32 v220, v220, s97, -v2
	v_fma_f32 v221, v221, s97, -v2
	v_fma_f32 v222, v222, s97, -v2
	v_fma_f32 v223, v223, s97, -v2
	v_fma_f32 v224, v224, s97, -v2
	v_fma_f32 v225, v225, s97, -v2
	v_fma_f32 v226, v226, s97, -v2
	v_fma_f32 v227, v227, s97, -v2
	s_waitcnt lgkmcnt(0)
	v_mfma_f32_32x32x16_bf16 v[34:49], v[174:177], v[178:181], v[34:49]
	v_exp_f32_e32 v220, v220
	v_exp_f32_e32 v221, v221
	v_exp_f32_e32 v222, v222
	v_exp_f32_e32 v223, v223
	v_exp_f32_e32 v224, v224
	v_exp_f32_e32 v225, v225
	v_exp_f32_e32 v226, v226
	v_exp_f32_e32 v227, v227
	v_add_f32_e32 v17, v222, v220
	v_add_f32_e32 v219, v223, v221
	v_add_f32_e32 v17, v224, v17
	v_add_f32_e32 v219, v225, v219
	v_add_f32_e32 v17, v226, v17
	v_add_f32_e32 v219, v227, v219
	v_cvt_pk_bf16_f32 v220, v220, v221
	v_cvt_pk_bf16_f32 v221, v222, v223
	v_cvt_pk_bf16_f32 v222, v224, v225
	v_cvt_pk_bf16_f32 v223, v226, v227
	s_nop 1
	v_mfma_f32_32x32x16_bf16 v[114:129], v[162:165], v[220:223], v[114:129]
	ds_read_b128 v[162:165], v201 offset:32768
	v_fma_f32 v228, v228, s97, -v2
	v_fma_f32 v229, v229, s97, -v2
	v_fma_f32 v230, v230, s97, -v2
	v_fma_f32 v231, v231, s97, -v2
	v_fma_f32 v232, v232, s97, -v2
	v_fma_f32 v233, v233, s97, -v2
	v_fma_f32 v234, v234, s97, -v2
	v_mfma_f32_32x32x16_bf16 v[82:97], v[166:169], v[220:223], v[82:97]
	ds_read_b128 v[166:169], v201 offset:36864
	v_fma_f32 v235, v235, s97, -v2
	v_exp_f32_e32 v228, v228
	v_exp_f32_e32 v229, v229
	v_exp_f32_e32 v230, v230
	v_exp_f32_e32 v231, v231
	v_exp_f32_e32 v232, v232
	v_exp_f32_e32 v233, v233
	v_mfma_f32_32x32x16_bf16 v[50:65], v[170:173], v[220:223], v[50:65]
	ds_read_b128 v[170:173], v201 offset:40960
	v_exp_f32_e32 v234, v234
	v_exp_f32_e32 v235, v235
	v_add_f32_e32 v17, v228, v17
	v_add_f32_e32 v219, v229, v219
	v_add_f32_e32 v17, v230, v17
	v_add_f32_e32 v219, v231, v219
	v_add_f32_e32 v17, v232, v17
	v_mfma_f32_32x32x16_bf16 v[18:33], v[174:177], v[220:223], v[18:33]
	ds_read_b128 v[174:177], v201 offset:45056
	v_add_f32_e32 v219, v233, v219
	v_add_f32_e32 v17, v234, v17
	v_add_f32_e32 v219, v235, v219
	v_cvt_pk_bf16_f32 v228, v228, v229
	v_cvt_pk_bf16_f32 v229, v230, v231
	v_cvt_pk_bf16_f32 v230, v232, v233
	v_cvt_pk_bf16_f32 v231, v234, v235
	s_waitcnt lgkmcnt(3)
	v_mfma_f32_32x32x16_bf16 v[130:145], v[162:165], v[12:15], v[130:145]
	v_fma_f32 v236, v236, s97, -v2
	v_fma_f32 v237, v237, s97, -v2
	v_fma_f32 v238, v238, s97, -v2
	v_fma_f32 v239, v239, s97, -v2
	v_mfma_f32_32x32x16_bf16 v[114:129], v[162:165], v[228:231], v[114:129]
	ds_read_b128 v[162:165], v202 offset:32768
	v_fma_f32 v240, v240, s97, -v2
	v_fma_f32 v241, v241, s97, -v2
	v_fma_f32 v242, v242, s97, -v2
	v_fma_f32 v243, v243, s97, -v2
	s_waitcnt lgkmcnt(3)
	v_mfma_f32_32x32x16_bf16 v[98:113], v[166:169], v[12:15], v[98:113]
	v_exp_f32_e32 v236, v236
	v_exp_f32_e32 v237, v237
	v_exp_f32_e32 v238, v238
	v_exp_f32_e32 v239, v239
	v_mfma_f32_32x32x16_bf16 v[82:97], v[166:169], v[228:231], v[82:97]
	ds_read_b128 v[166:169], v202 offset:36864
	v_exp_f32_e32 v240, v240
	v_exp_f32_e32 v241, v241
	v_exp_f32_e32 v242, v242
	v_exp_f32_e32 v243, v243
	s_waitcnt lgkmcnt(3)
	v_mfma_f32_32x32x16_bf16 v[66:81], v[170:173], v[12:15], v[66:81]
	v_add_f32_e32 v17, v236, v17
	v_add_f32_e32 v219, v237, v219
	v_add_f32_e32 v17, v238, v17
	v_add_f32_e32 v219, v239, v219
	v_mfma_f32_32x32x16_bf16 v[50:65], v[170:173], v[228:231], v[50:65]
	ds_read_b128 v[170:173], v202 offset:40960
	v_add_f32_e32 v17, v240, v17
	v_add_f32_e32 v219, v241, v219
	v_add_f32_e32 v17, v242, v17
	v_add_f32_e32 v219, v243, v219
	s_waitcnt lgkmcnt(3)
	v_mfma_f32_32x32x16_bf16 v[34:49], v[174:177], v[12:15], v[34:49]
	v_cvt_pk_bf16_f32 v236, v236, v237
	v_cvt_pk_bf16_f32 v237, v238, v239
	v_cvt_pk_bf16_f32 v238, v240, v241
	v_cvt_pk_bf16_f32 v239, v242, v243
	v_mfma_f32_32x32x16_bf16 v[18:33], v[174:177], v[228:231], v[18:33]
	ds_read_b128 v[174:177], v202 offset:45056
	s_waitcnt lgkmcnt(3)
	v_mfma_f32_32x32x16_bf16 v[114:129], v[162:165], v[236:239], v[114:129]
	v_fma_f32 v216, v146, s97, -v207
	v_fma_f32 v217, v147, s97, -v207
	v_fma_f32 v252, v148, s97, -v207
	v_fma_f32 v253, v149, s97, -v207
	v_exp_f32_e32 v216, v216
	v_exp_f32_e32 v217, v217
	v_exp_f32_e32 v252, v252
	v_exp_f32_e32 v253, v253
	v_cvt_pk_bf16_f32 v8, v216, v217
	v_cvt_pk_bf16_f32 v9, v252, v253
	v_add_f32_e32 v254, v252, v216
	v_add_f32_e32 v204, v253, v217
	s_waitcnt lgkmcnt(2)
	v_mfma_f32_32x32x16_bf16 v[82:97], v[166:169], v[236:239], v[82:97]
	v_fma_f32 v216, v150, s97, -v207
	v_fma_f32 v217, v151, s97, -v207
	v_fma_f32 v252, v152, s97, -v207
	v_fma_f32 v253, v153, s97, -v207
	v_exp_f32_e32 v216, v216
	v_exp_f32_e32 v217, v217
	v_exp_f32_e32 v252, v252
	v_exp_f32_e32 v253, v253
	v_add_f32_e32 v254, v216, v254
	v_add_f32_e32 v204, v217, v204
	v_cvt_pk_bf16_f32 v10, v216, v217
	v_cvt_pk_bf16_f32 v11, v252, v253
	v_add_f32_e32 v254, v252, v254
	v_add_f32_e32 v204, v253, v204
	s_waitcnt lgkmcnt(1)
	v_mfma_f32_32x32x16_bf16 v[50:65], v[170:173], v[236:239], v[50:65]
	v_fma_f32 v216, v154, s97, -v207
	v_fma_f32 v217, v155, s97, -v207
	v_fma_f32 v252, v156, s97, -v207
	v_fma_f32 v253, v157, s97, -v207
	v_exp_f32_e32 v216, v216
	v_exp_f32_e32 v217, v217
	v_exp_f32_e32 v252, v252
	v_exp_f32_e32 v253, v253
	v_add_f32_e32 v254, v216, v254
	v_add_f32_e32 v204, v217, v204
	v_cvt_pk_bf16_f32 v4, v216, v217
	v_cvt_pk_bf16_f32 v5, v252, v253
	v_add_f32_e32 v254, v252, v254
	v_add_f32_e32 v204, v253, v204
	s_waitcnt lgkmcnt(0)
	v_mfma_f32_32x32x16_bf16 v[18:33], v[174:177], v[236:239], v[18:33]
	v_fma_f32 v216, v158, s97, -v207
	v_fma_f32 v217, v159, s97, -v207
	v_fma_f32 v252, v160, s97, -v207
	v_fma_f32 v253, v161, s97, -v207
	v_exp_f32_e32 v216, v216
	v_exp_f32_e32 v217, v217
	v_exp_f32_e32 v252, v252
	v_exp_f32_e32 v253, v253
	v_add_f32_e32 v254, v216, v254
	v_add_f32_e32 v204, v217, v204
	v_cvt_pk_bf16_f32 v6, v216, v217
	v_cvt_pk_bf16_f32 v7, v252, v253
	v_add_f32_e32 v254, v252, v254
	v_add_f32_e32 v204, v253, v204
	v_add_f32_e32 v254, v254, v204
	v_cmp_lt_f32_e32 vcc, 0x43800000, v254
	s_cmp_lg_u64 vcc, 0
	s_cbranch_scc1 .Lat_rare0b
